# v025 + epi_rownorm LDS ladders batched in the cmp tiles and the phase-3 in-proj epilogues
# speedup vs baseline: 1.0031x; 1.0031x over previous
; #define TIDX (tid_launder())
; DI void epi_rownorm(const float* Ct, float* rn, int W) {
;   const int row = TIDX >> 1, grp = TIDX & 1;
;   float ss = 0.f;
;   for (int c0 = 0; c0 < 64; ++c0) { const int c = (c0 + row) & 63; const float v = Ct[row * 132 + grp * 64 + c]; ss += v * v; }
;   if (W == 128) { ss += __shfl_xor(ss, 1); ss *= 0.5f; }
;   rn[row * 2 + grp] = rsqrtf(ss * (1.f / 64.f) + 1e-6f);
.LBB0_788:
	s_andn2_b64 vcc, exec, s[0:1]
	s_cbranch_vccnz .LBB0_777
	v_mov_b32_e32 v0, v230
	v_mov_b32_e32 v2, v230
	s_mov_b32 s0, 0x3ffffffe
	v_ashrrev_i32_e32 v3, 1, v0
	v_and_b32_e32 v2, 1, v2
	v_mul_lo_u32 v4, v3, s79
	v_add_u32_e32 v7, 55, v3
	v_lshl_add_u32 v4, v2, 8, v4
	v_and_b32_e32 v5, 63, v3
	v_and_b32_e32 v7, 63, v7
	v_lshl_add_u32 v5, v5, 2, v4
	v_lshl_add_u32 v7, v7, 2, v4
	ds_read_b32 v6, v5
	ds_read_b32 v7, v7
	v_add_u32_e32 v5, 1, v3
	v_and_b32_e32 v5, 63, v5
	v_lshl_add_u32 v5, v5, 2, v4
	ds_read_b32 v5, v5
	v_and_or_b32 v0, v0, s0, v2
	v_lshl_add_u32 v0, v0, 2, v237
	v_mov_b32_e32 v10, v230
	s_waitcnt lgkmcnt(0)
	v_mul_f32_e32 v5, v5, v5
	v_fmac_f32_e32 v5, v6, v6
	v_add_u32_e32 v6, 2, v3
	v_and_b32_e32 v6, 63, v6
	v_lshl_add_u32 v6, v6, 2, v4
	ds_read_b32 v6, v6
	v_add_u32_e32 v34, 3, v3
	v_and_b32_e32 v34, 63, v34
	v_lshl_add_u32 v34, v34, 2, v4
	ds_read_b32 v34, v34
	v_add_u32_e32 v35, 4, v3
	v_and_b32_e32 v35, 63, v35
	v_lshl_add_u32 v35, v35, 2, v4
	ds_read_b32 v35, v35
	v_add_u32_e32 v36, 5, v3
	v_and_b32_e32 v36, 63, v36
	v_lshl_add_u32 v36, v36, 2, v4
	ds_read_b32 v36, v36
	v_add_u32_e32 v37, 6, v3
	v_and_b32_e32 v37, 63, v37
	v_lshl_add_u32 v37, v37, 2, v4
	ds_read_b32 v37, v37
	v_add_u32_e32 v38, 7, v3
	v_and_b32_e32 v38, 63, v38
	v_lshl_add_u32 v38, v38, 2, v4
	ds_read_b32 v38, v38
	v_add_u32_e32 v39, 8, v3
	v_and_b32_e32 v39, 63, v39
	v_lshl_add_u32 v39, v39, 2, v4
	ds_read_b32 v39, v39
	v_add_u32_e32 v40, 9, v3
	v_and_b32_e32 v40, 63, v40
	v_lshl_add_u32 v40, v40, 2, v4
	ds_read_b32 v40, v40
	v_add_u32_e32 v41, 10, v3
	v_and_b32_e32 v41, 63, v41
	v_lshl_add_u32 v41, v41, 2, v4
	ds_read_b32 v41, v41
	v_add_u32_e32 v42, 11, v3
	v_and_b32_e32 v42, 63, v42
	v_lshl_add_u32 v42, v42, 2, v4
	ds_read_b32 v42, v42
	v_add_u32_e32 v43, 12, v3
	v_and_b32_e32 v43, 63, v43
	v_lshl_add_u32 v43, v43, 2, v4
	ds_read_b32 v43, v43
	v_add_u32_e32 v44, 13, v3
	v_and_b32_e32 v44, 63, v44
	v_lshl_add_u32 v44, v44, 2, v4
	ds_read_b32 v44, v44
	v_add_u32_e32 v45, 14, v3
	v_and_b32_e32 v45, 63, v45
	v_lshl_add_u32 v45, v45, 2, v4
	ds_read_b32 v45, v45
	s_waitcnt lgkmcnt(12)
	v_fmac_f32_e32 v5, v6, v6
	s_waitcnt lgkmcnt(11)
	v_fmac_f32_e32 v5, v34, v34
	s_waitcnt lgkmcnt(10)
	v_fmac_f32_e32 v5, v35, v35
	s_waitcnt lgkmcnt(9)
	v_fmac_f32_e32 v5, v36, v36
	s_waitcnt lgkmcnt(8)
	v_fmac_f32_e32 v5, v37, v37
	s_waitcnt lgkmcnt(7)
	v_fmac_f32_e32 v5, v38, v38
	s_waitcnt lgkmcnt(6)
	v_fmac_f32_e32 v5, v39, v39
	s_waitcnt lgkmcnt(5)
	v_fmac_f32_e32 v5, v40, v40
	s_waitcnt lgkmcnt(4)
	v_fmac_f32_e32 v5, v41, v41
	s_waitcnt lgkmcnt(3)
	v_fmac_f32_e32 v5, v42, v42
	s_waitcnt lgkmcnt(2)
	v_fmac_f32_e32 v5, v43, v43
	s_waitcnt lgkmcnt(1)
	v_fmac_f32_e32 v5, v44, v44
	s_waitcnt lgkmcnt(0)
	v_fmac_f32_e32 v5, v45, v45
	v_add_u32_e32 v6, 15, v3
	v_and_b32_e32 v6, 63, v6
	v_lshl_add_u32 v6, v6, 2, v4
	ds_read_b32 v6, v6
	v_add_u32_e32 v34, 16, v3
	v_and_b32_e32 v34, 63, v34
	v_lshl_add_u32 v34, v34, 2, v4
	ds_read_b32 v34, v34
	v_add_u32_e32 v35, 17, v3
	v_and_b32_e32 v35, 63, v35
	v_lshl_add_u32 v35, v35, 2, v4
	ds_read_b32 v35, v35
	v_add_u32_e32 v36, 18, v3
	v_and_b32_e32 v36, 63, v36
	v_lshl_add_u32 v36, v36, 2, v4
	ds_read_b32 v36, v36
	v_add_u32_e32 v37, 19, v3
	v_and_b32_e32 v37, 63, v37
	v_lshl_add_u32 v37, v37, 2, v4
	ds_read_b32 v37, v37
	v_add_u32_e32 v38, 20, v3
	v_and_b32_e32 v38, 63, v38
	v_lshl_add_u32 v38, v38, 2, v4
	ds_read_b32 v38, v38
	v_add_u32_e32 v39, 21, v3
	v_and_b32_e32 v39, 63, v39
	v_lshl_add_u32 v39, v39, 2, v4
	ds_read_b32 v39, v39
	v_add_u32_e32 v40, 22, v3
	v_and_b32_e32 v40, 63, v40
	v_lshl_add_u32 v40, v40, 2, v4
	ds_read_b32 v40, v40
	v_add_u32_e32 v41, 23, v3
	v_and_b32_e32 v41, 63, v41
	v_lshl_add_u32 v41, v41, 2, v4
	ds_read_b32 v41, v41
	v_add_u32_e32 v42, 24, v3
	v_and_b32_e32 v42, 63, v42
	v_lshl_add_u32 v42, v42, 2, v4
	ds_read_b32 v42, v42
	v_add_u32_e32 v43, 25, v3
	v_and_b32_e32 v43, 63, v43
	v_lshl_add_u32 v43, v43, 2, v4
	ds_read_b32 v43, v43
	v_add_u32_e32 v44, 26, v3
	v_and_b32_e32 v44, 63, v44
	v_lshl_add_u32 v44, v44, 2, v4
	ds_read_b32 v44, v44
	v_add_u32_e32 v45, 27, v3
	v_and_b32_e32 v45, 63, v45
	v_lshl_add_u32 v45, v45, 2, v4
	ds_read_b32 v45, v45
	s_waitcnt lgkmcnt(12)
	v_fmac_f32_e32 v5, v6, v6
	s_waitcnt lgkmcnt(11)
	v_fmac_f32_e32 v5, v34, v34
	s_waitcnt lgkmcnt(10)
	v_fmac_f32_e32 v5, v35, v35
	s_waitcnt lgkmcnt(9)
	v_fmac_f32_e32 v5, v36, v36
	s_waitcnt lgkmcnt(8)
	v_fmac_f32_e32 v5, v37, v37
	s_waitcnt lgkmcnt(7)
	v_fmac_f32_e32 v5, v38, v38
	s_waitcnt lgkmcnt(6)
	v_fmac_f32_e32 v5, v39, v39
	s_waitcnt lgkmcnt(5)
	v_fmac_f32_e32 v5, v40, v40
	s_waitcnt lgkmcnt(4)
	v_fmac_f32_e32 v5, v41, v41
	s_waitcnt lgkmcnt(3)
	v_fmac_f32_e32 v5, v42, v42
	s_waitcnt lgkmcnt(2)
	v_fmac_f32_e32 v5, v43, v43
	s_waitcnt lgkmcnt(1)
	v_fmac_f32_e32 v5, v44, v44
	s_waitcnt lgkmcnt(0)
	v_fmac_f32_e32 v5, v45, v45
	v_add_u32_e32 v6, 28, v3
	v_and_b32_e32 v6, 63, v6
	v_lshl_add_u32 v6, v6, 2, v4
	ds_read_b32 v6, v6
	v_add_u32_e32 v34, 29, v3
	v_and_b32_e32 v34, 63, v34
	v_lshl_add_u32 v34, v34, 2, v4
	ds_read_b32 v34, v34
	v_add_u32_e32 v35, 30, v3
	v_and_b32_e32 v35, 63, v35
	v_lshl_add_u32 v35, v35, 2, v4
	ds_read_b32 v35, v35
	v_add_u32_e32 v36, 31, v3
	v_and_b32_e32 v36, 63, v36
	v_lshl_add_u32 v36, v36, 2, v4
	ds_read_b32 v36, v36
	v_bitop3_b32 v37, v3, 32, 63 bitop3:0x6c
	v_lshl_add_u32 v37, v37, 2, v4
	ds_read_b32 v37, v37
	v_add_u32_e32 v38, 33, v3
	v_and_b32_e32 v38, 63, v38
	v_lshl_add_u32 v38, v38, 2, v4
	ds_read_b32 v38, v38
	v_add_u32_e32 v39, 34, v3
	v_and_b32_e32 v39, 63, v39
	v_lshl_add_u32 v39, v39, 2, v4
	ds_read_b32 v39, v39
	v_add_u32_e32 v40, 35, v3
	v_and_b32_e32 v40, 63, v40
	v_lshl_add_u32 v40, v40, 2, v4
	ds_read_b32 v40, v40
	v_add_u32_e32 v41, 36, v3
	v_and_b32_e32 v41, 63, v41
	v_lshl_add_u32 v41, v41, 2, v4
	ds_read_b32 v41, v41
	v_add_u32_e32 v42, 37, v3
	v_and_b32_e32 v42, 63, v42
	v_lshl_add_u32 v42, v42, 2, v4
	ds_read_b32 v42, v42
	v_add_u32_e32 v43, 38, v3
	v_and_b32_e32 v43, 63, v43
	v_lshl_add_u32 v43, v43, 2, v4
	ds_read_b32 v43, v43
	v_add_u32_e32 v44, 39, v3
	v_and_b32_e32 v44, 63, v44
	v_lshl_add_u32 v44, v44, 2, v4
	ds_read_b32 v44, v44
	v_add_u32_e32 v45, 40, v3
	v_and_b32_e32 v45, 63, v45
	v_lshl_add_u32 v45, v45, 2, v4
	ds_read_b32 v45, v45
	s_waitcnt lgkmcnt(12)
; #define TIDX (tid_launder())
; DI void epi_rownorm(const float* Ct, float* rn, int W) {
;   const int row = TIDX >> 1, grp = TIDX & 1;
;   float ss = 0.f;
;   for (int c0 = 0; c0 < 64; ++c0) { const int c = (c0 + row) & 63; const float v = Ct[row * 132 + grp * 64 + c]; ss += v * v; }
;   if (W == 128) { ss += __shfl_xor(ss, 1); ss *= 0.5f; }
;   rn[row * 2 + grp] = rsqrtf(ss * (1.f / 64.f) + 1e-6f);
;   __syncthreads();
; DI void cmp2_tile(const Params& p, int l, int kv, int mt, char* smem) {
;     ...
;   if (kv == 0) {
;     epi_rownorm(Ct, rn, 64);
;     const float* g = p.c_k_norm + (l * 3 + 0) * 64;
;     for (int idx = TIDX; idx < 128 * 64; idx += 256) {
	v_fmac_f32_e32 v5, v6, v6
	s_waitcnt lgkmcnt(11)
	v_fmac_f32_e32 v5, v34, v34
	s_waitcnt lgkmcnt(10)
	v_fmac_f32_e32 v5, v35, v35
	s_waitcnt lgkmcnt(9)
	v_fmac_f32_e32 v5, v36, v36
	s_waitcnt lgkmcnt(8)
	v_fmac_f32_e32 v5, v37, v37
	s_waitcnt lgkmcnt(7)
	v_fmac_f32_e32 v5, v38, v38
	s_waitcnt lgkmcnt(6)
	v_fmac_f32_e32 v5, v39, v39
	s_waitcnt lgkmcnt(5)
	v_fmac_f32_e32 v5, v40, v40
	s_waitcnt lgkmcnt(4)
	v_fmac_f32_e32 v5, v41, v41
	s_waitcnt lgkmcnt(3)
	v_fmac_f32_e32 v5, v42, v42
	s_waitcnt lgkmcnt(2)
	v_fmac_f32_e32 v5, v43, v43
	s_waitcnt lgkmcnt(1)
	v_fmac_f32_e32 v5, v44, v44
	s_waitcnt lgkmcnt(0)
	v_fmac_f32_e32 v5, v45, v45
	v_add_u32_e32 v6, 41, v3
	v_and_b32_e32 v6, 63, v6
	v_lshl_add_u32 v6, v6, 2, v4
	ds_read_b32 v6, v6
	v_add_u32_e32 v34, 42, v3
	v_and_b32_e32 v34, 63, v34
	v_lshl_add_u32 v34, v34, 2, v4
	ds_read_b32 v34, v34
	v_add_u32_e32 v35, 43, v3
	v_and_b32_e32 v35, 63, v35
	v_lshl_add_u32 v35, v35, 2, v4
	ds_read_b32 v35, v35
	v_add_u32_e32 v36, 44, v3
	v_and_b32_e32 v36, 63, v36
	v_lshl_add_u32 v36, v36, 2, v4
	ds_read_b32 v36, v36
	v_add_u32_e32 v37, 45, v3
	v_and_b32_e32 v37, 63, v37
	v_lshl_add_u32 v37, v37, 2, v4
	ds_read_b32 v37, v37
	v_add_u32_e32 v38, 46, v3
	v_and_b32_e32 v38, 63, v38
	v_lshl_add_u32 v38, v38, 2, v4
	ds_read_b32 v38, v38
	v_add_u32_e32 v39, 47, v3
	v_and_b32_e32 v39, 63, v39
	v_lshl_add_u32 v39, v39, 2, v4
	ds_read_b32 v39, v39
	v_add_u32_e32 v40, 48, v3
	v_and_b32_e32 v40, 63, v40
	v_lshl_add_u32 v40, v40, 2, v4
	ds_read_b32 v40, v40
	v_add_u32_e32 v41, 49, v3
	v_and_b32_e32 v41, 63, v41
	v_lshl_add_u32 v41, v41, 2, v4
	ds_read_b32 v41, v41
	v_add_u32_e32 v42, 50, v3
	v_and_b32_e32 v42, 63, v42
	v_lshl_add_u32 v42, v42, 2, v4
	ds_read_b32 v42, v42
	v_add_u32_e32 v43, 51, v3
	v_and_b32_e32 v43, 63, v43
	v_lshl_add_u32 v43, v43, 2, v4
	ds_read_b32 v43, v43
	v_add_u32_e32 v44, 52, v3
	v_and_b32_e32 v44, 63, v44
	v_lshl_add_u32 v44, v44, 2, v4
	ds_read_b32 v44, v44
	v_add_u32_e32 v45, 53, v3
	v_and_b32_e32 v45, 63, v45
	v_lshl_add_u32 v45, v45, 2, v4
	ds_read_b32 v45, v45
	s_waitcnt lgkmcnt(12)
	v_fmac_f32_e32 v5, v6, v6
	s_waitcnt lgkmcnt(11)
	v_fmac_f32_e32 v5, v34, v34
	s_waitcnt lgkmcnt(10)
	v_fmac_f32_e32 v5, v35, v35
	s_waitcnt lgkmcnt(9)
	v_fmac_f32_e32 v5, v36, v36
	s_waitcnt lgkmcnt(8)
	v_fmac_f32_e32 v5, v37, v37
	s_waitcnt lgkmcnt(7)
	v_fmac_f32_e32 v5, v38, v38
	s_waitcnt lgkmcnt(6)
	v_fmac_f32_e32 v5, v39, v39
	s_waitcnt lgkmcnt(5)
	v_fmac_f32_e32 v5, v40, v40
	s_waitcnt lgkmcnt(4)
	v_fmac_f32_e32 v5, v41, v41
	s_waitcnt lgkmcnt(3)
	v_fmac_f32_e32 v5, v42, v42
	s_waitcnt lgkmcnt(2)
	v_fmac_f32_e32 v5, v43, v43
	s_waitcnt lgkmcnt(1)
	v_fmac_f32_e32 v5, v44, v44
	s_waitcnt lgkmcnt(0)
	v_fmac_f32_e32 v5, v45, v45
	v_add_u32_e32 v6, 54, v3
	v_and_b32_e32 v6, 63, v6
	v_lshl_add_u32 v6, v6, 2, v4
	ds_read_b32 v6, v6
	s_waitcnt lgkmcnt(0)
	v_pk_mul_f32 v[6:7], v[6:7], v[6:7]
	s_nop 0
	v_add_f32_e32 v5, v5, v6
	v_add_f32_e32 v5, v5, v7
	v_add_u32_e32 v6, 56, v3
	v_add_u32_e32 v7, 57, v3
	v_and_b32_e32 v6, 63, v6
	v_and_b32_e32 v7, 63, v7
	v_lshl_add_u32 v6, v6, 2, v4
	v_lshl_add_u32 v7, v7, 2, v4
	ds_read_b32 v6, v6
	ds_read_b32 v7, v7
	s_waitcnt lgkmcnt(0)
	v_pk_mul_f32 v[6:7], v[6:7], v[6:7]
	s_nop 0
	v_add_f32_e32 v5, v5, v6
	v_add_f32_e32 v5, v5, v7
	v_add_u32_e32 v6, 58, v3
	v_add_u32_e32 v7, 59, v3
	v_and_b32_e32 v6, 63, v6
	v_and_b32_e32 v7, 63, v7
	v_lshl_add_u32 v6, v6, 2, v4
	v_lshl_add_u32 v7, v7, 2, v4
	ds_read_b32 v6, v6
	ds_read_b32 v7, v7
	s_waitcnt lgkmcnt(0)
	v_pk_mul_f32 v[6:7], v[6:7], v[6:7]
	s_nop 0
	v_add_f32_e32 v5, v5, v6
	v_add_f32_e32 v5, v5, v7
	v_add_u32_e32 v6, 60, v3
	v_add_u32_e32 v7, 61, v3
	v_and_b32_e32 v6, 63, v6
	v_and_b32_e32 v7, 63, v7
	v_lshl_add_u32 v6, v6, 2, v4
	v_lshl_add_u32 v7, v7, 2, v4
	ds_read_b32 v6, v6
	ds_read_b32 v7, v7
	s_waitcnt lgkmcnt(0)
	v_pk_mul_f32 v[6:7], v[6:7], v[6:7]
	s_nop 0
	v_add_f32_e32 v5, v5, v6
	v_add_f32_e32 v8, v5, v7
	v_add_u32_e32 v5, 62, v3
	v_add_u32_e32 v3, -1, v3
	v_and_b32_e32 v5, 63, v5
	v_and_b32_e32 v3, 63, v3
	v_lshl_add_u32 v5, v5, 2, v4
	v_lshl_add_u32 v3, v3, 2, v4
	ds_read_b32 v6, v5
	ds_read_b32 v7, v3
	s_waitcnt lgkmcnt(0)
	v_pk_mul_f32 v[4:5], v[6:7], v[6:7]
	s_nop 0
	v_add_f32_e32 v3, v8, v4
	v_add_f32_e32 v3, v3, v5
	v_fmamk_f32 v3, v3, 0x3c800000, v244
	v_cmp_gt_f32_e32 vcc, s14, v3
	v_mul_f32_e32 v4, 0x4b800000, v3
	s_nop 0
	v_cndmask_b32_e32 v3, v3, v4, vcc
	v_rsq_f32_e32 v3, v3
	s_nop 0
	v_mul_f32_e32 v4, 0x45800000, v3
	v_cndmask_b32_e32 v3, v3, v4, vcc
	ds_write_b32 v0, v3
	s_waitcnt lgkmcnt(0)
	s_barrier
	s_nop 0
	v_cmp_gt_i32_e32 vcc, s80, v10
	s_and_saveexec_b64 s[0:1], vcc
	s_cbranch_execz .LBB0_776
	v_and_b32_e32 v0, 63, v10
	v_readlane_b32 s2, v254, 7
	v_lshlrev_b32_e32 v2, 2, v0
	v_mov_b32_e32 v3, v1
	v_readlane_b32 s3, v254, 8
	v_and_b32_e32 v6, 7, v10
	s_nop 0
	v_lshl_add_u64 v[4:5], s[2:3], 0, v[2:3]
	v_lshlrev_b32_e32 v3, 5, v0
	v_or3_b32 v0, v6, v3, s36
	s_movk_i32 s2, 0x700
	v_and_or_b32 v3, v3, s2, v6
	s_mov_b64 s[2:3], 0
	v_lshlrev_b32_e32 v6, 1, v0
	s_branch .LBB0_792

; #define TIDX (tid_launder())
; DI void epi_rownorm(const float* Ct, float* rn, int W) {
;   const int row = TIDX >> 1, grp = TIDX & 1;
;   float ss = 0.f;
;   for (int c0 = 0; c0 < 64; ++c0) { const int c = (c0 + row) & 63; const float v = Ct[row * 132 + grp * 64 + c]; ss += v * v; }
;   if (W == 128) { ss += __shfl_xor(ss, 1); ss *= 0.5f; }
;   rn[row * 2 + grp] = rsqrtf(ss * (1.f / 64.f) + 1e-6f);
;   __syncthreads();
.LBB0_1260:
	s_and_b64 vcc, exec, s[0:1]
	s_cbranch_vccz .LBB0_1310
	v_mov_b32_e32 v0, v230
	v_mov_b32_e32 v2, v230
	s_mov_b32 s0, 0x800000
	v_ashrrev_i32_e32 v3, 1, v0
	v_and_b32_e32 v2, 1, v2
	v_mul_lo_u32 v4, v3, s79
	v_add_u32_e32 v7, 55, v3
	v_lshl_add_u32 v4, v2, 8, v4
	v_and_b32_e32 v5, 63, v3
	v_and_b32_e32 v7, 63, v7
	v_lshl_add_u32 v5, v5, 2, v4
	v_lshl_add_u32 v7, v7, 2, v4
	ds_read_b32 v6, v5
	ds_read_b32 v7, v7
	v_add_u32_e32 v5, 1, v3
	v_and_b32_e32 v5, 63, v5
	v_lshl_add_u32 v5, v5, 2, v4
	ds_read_b32 v5, v5
	v_mov_b32_e32 v18, v230
	s_mov_b64 s[4:5], -1
	v_mov_b32_e32 v11, 1.0
	v_mov_b32_e32 v10, 1.0
	s_waitcnt lgkmcnt(0)
	v_mul_f32_e32 v5, v5, v5
	v_fmac_f32_e32 v5, v6, v6
	v_add_u32_e32 v6, 2, v3
	v_and_b32_e32 v6, 63, v6
	v_lshl_add_u32 v6, v6, 2, v4
	ds_read_b32 v6, v6
	v_add_u32_e32 v34, 3, v3
	v_and_b32_e32 v34, 63, v34
	v_lshl_add_u32 v34, v34, 2, v4
	ds_read_b32 v34, v34
	v_add_u32_e32 v35, 4, v3
	v_and_b32_e32 v35, 63, v35
	v_lshl_add_u32 v35, v35, 2, v4
	ds_read_b32 v35, v35
	v_add_u32_e32 v36, 5, v3
	v_and_b32_e32 v36, 63, v36
	v_lshl_add_u32 v36, v36, 2, v4
	ds_read_b32 v36, v36
	v_add_u32_e32 v37, 6, v3
	v_and_b32_e32 v37, 63, v37
	v_lshl_add_u32 v37, v37, 2, v4
	ds_read_b32 v37, v37
	v_add_u32_e32 v38, 7, v3
	v_and_b32_e32 v38, 63, v38
	v_lshl_add_u32 v38, v38, 2, v4
	ds_read_b32 v38, v38
	v_add_u32_e32 v39, 8, v3
	v_and_b32_e32 v39, 63, v39
	v_lshl_add_u32 v39, v39, 2, v4
	ds_read_b32 v39, v39
	v_add_u32_e32 v40, 9, v3
	v_and_b32_e32 v40, 63, v40
	v_lshl_add_u32 v40, v40, 2, v4
	ds_read_b32 v40, v40
	v_add_u32_e32 v41, 10, v3
	v_and_b32_e32 v41, 63, v41
	v_lshl_add_u32 v41, v41, 2, v4
	ds_read_b32 v41, v41
	v_add_u32_e32 v42, 11, v3
	v_and_b32_e32 v42, 63, v42
	v_lshl_add_u32 v42, v42, 2, v4
	ds_read_b32 v42, v42
	v_add_u32_e32 v43, 12, v3
	v_and_b32_e32 v43, 63, v43
	v_lshl_add_u32 v43, v43, 2, v4
	ds_read_b32 v43, v43
	v_add_u32_e32 v44, 13, v3
	v_and_b32_e32 v44, 63, v44
	v_lshl_add_u32 v44, v44, 2, v4
	ds_read_b32 v44, v44
	v_add_u32_e32 v45, 14, v3
	v_and_b32_e32 v45, 63, v45
	v_lshl_add_u32 v45, v45, 2, v4
	ds_read_b32 v45, v45
	s_waitcnt lgkmcnt(12)
	v_fmac_f32_e32 v5, v6, v6
	s_waitcnt lgkmcnt(11)
	v_fmac_f32_e32 v5, v34, v34
	s_waitcnt lgkmcnt(10)
	v_fmac_f32_e32 v5, v35, v35
	s_waitcnt lgkmcnt(9)
	v_fmac_f32_e32 v5, v36, v36
	s_waitcnt lgkmcnt(8)
	v_fmac_f32_e32 v5, v37, v37
	s_waitcnt lgkmcnt(7)
	v_fmac_f32_e32 v5, v38, v38
	s_waitcnt lgkmcnt(6)
	v_fmac_f32_e32 v5, v39, v39
	s_waitcnt lgkmcnt(5)
	v_fmac_f32_e32 v5, v40, v40
	s_waitcnt lgkmcnt(4)
	v_fmac_f32_e32 v5, v41, v41
	s_waitcnt lgkmcnt(3)
	v_fmac_f32_e32 v5, v42, v42
	s_waitcnt lgkmcnt(2)
	v_fmac_f32_e32 v5, v43, v43
	s_waitcnt lgkmcnt(1)
	v_fmac_f32_e32 v5, v44, v44
	s_waitcnt lgkmcnt(0)
	v_fmac_f32_e32 v5, v45, v45
	v_add_u32_e32 v6, 15, v3
	v_and_b32_e32 v6, 63, v6
	v_lshl_add_u32 v6, v6, 2, v4
	ds_read_b32 v6, v6
	v_add_u32_e32 v34, 16, v3
	v_and_b32_e32 v34, 63, v34
	v_lshl_add_u32 v34, v34, 2, v4
	ds_read_b32 v34, v34
	v_add_u32_e32 v35, 17, v3
	v_and_b32_e32 v35, 63, v35
	v_lshl_add_u32 v35, v35, 2, v4
	ds_read_b32 v35, v35
	v_add_u32_e32 v36, 18, v3
	v_and_b32_e32 v36, 63, v36
	v_lshl_add_u32 v36, v36, 2, v4
	ds_read_b32 v36, v36
	v_add_u32_e32 v37, 19, v3
	v_and_b32_e32 v37, 63, v37
	v_lshl_add_u32 v37, v37, 2, v4
	ds_read_b32 v37, v37
	v_add_u32_e32 v38, 20, v3
	v_and_b32_e32 v38, 63, v38
	v_lshl_add_u32 v38, v38, 2, v4
	ds_read_b32 v38, v38
	v_add_u32_e32 v39, 21, v3
	v_and_b32_e32 v39, 63, v39
	v_lshl_add_u32 v39, v39, 2, v4
	ds_read_b32 v39, v39
	v_add_u32_e32 v40, 22, v3
	v_and_b32_e32 v40, 63, v40
	v_lshl_add_u32 v40, v40, 2, v4
	ds_read_b32 v40, v40
	v_add_u32_e32 v41, 23, v3
	v_and_b32_e32 v41, 63, v41
	v_lshl_add_u32 v41, v41, 2, v4
	ds_read_b32 v41, v41
	v_add_u32_e32 v42, 24, v3
	v_and_b32_e32 v42, 63, v42
	v_lshl_add_u32 v42, v42, 2, v4
	ds_read_b32 v42, v42
	v_add_u32_e32 v43, 25, v3
	v_and_b32_e32 v43, 63, v43
	v_lshl_add_u32 v43, v43, 2, v4
	ds_read_b32 v43, v43
	v_add_u32_e32 v44, 26, v3
	v_and_b32_e32 v44, 63, v44
	v_lshl_add_u32 v44, v44, 2, v4
	ds_read_b32 v44, v44
	v_add_u32_e32 v45, 27, v3
	v_and_b32_e32 v45, 63, v45
	v_lshl_add_u32 v45, v45, 2, v4
	ds_read_b32 v45, v45
	s_waitcnt lgkmcnt(12)
	v_fmac_f32_e32 v5, v6, v6
	s_waitcnt lgkmcnt(11)
	v_fmac_f32_e32 v5, v34, v34
	s_waitcnt lgkmcnt(10)
	v_fmac_f32_e32 v5, v35, v35
	s_waitcnt lgkmcnt(9)
	v_fmac_f32_e32 v5, v36, v36
	s_waitcnt lgkmcnt(8)
	v_fmac_f32_e32 v5, v37, v37
	s_waitcnt lgkmcnt(7)
	v_fmac_f32_e32 v5, v38, v38
	s_waitcnt lgkmcnt(6)
	v_fmac_f32_e32 v5, v39, v39
	s_waitcnt lgkmcnt(5)
	v_fmac_f32_e32 v5, v40, v40
	s_waitcnt lgkmcnt(4)
	v_fmac_f32_e32 v5, v41, v41
	s_waitcnt lgkmcnt(3)
	v_fmac_f32_e32 v5, v42, v42
	s_waitcnt lgkmcnt(2)
	v_fmac_f32_e32 v5, v43, v43
	s_waitcnt lgkmcnt(1)
	v_fmac_f32_e32 v5, v44, v44
	s_waitcnt lgkmcnt(0)
	v_fmac_f32_e32 v5, v45, v45
	v_add_u32_e32 v6, 28, v3
	v_and_b32_e32 v6, 63, v6
	v_lshl_add_u32 v6, v6, 2, v4
	ds_read_b32 v6, v6
	v_add_u32_e32 v34, 29, v3
	v_and_b32_e32 v34, 63, v34
	v_lshl_add_u32 v34, v34, 2, v4
	ds_read_b32 v34, v34
	v_add_u32_e32 v35, 30, v3
	v_and_b32_e32 v35, 63, v35
	v_lshl_add_u32 v35, v35, 2, v4
	ds_read_b32 v35, v35
	v_add_u32_e32 v36, 31, v3
	v_and_b32_e32 v36, 63, v36
	v_lshl_add_u32 v36, v36, 2, v4
	ds_read_b32 v36, v36
	v_bitop3_b32 v37, v3, 32, 63 bitop3:0x6c
	v_lshl_add_u32 v37, v37, 2, v4
	ds_read_b32 v37, v37
	v_add_u32_e32 v38, 33, v3
	v_and_b32_e32 v38, 63, v38
	v_lshl_add_u32 v38, v38, 2, v4
	ds_read_b32 v38, v38
	v_add_u32_e32 v39, 34, v3
	v_and_b32_e32 v39, 63, v39
	v_lshl_add_u32 v39, v39, 2, v4
	ds_read_b32 v39, v39
	v_add_u32_e32 v40, 35, v3
	v_and_b32_e32 v40, 63, v40
	v_lshl_add_u32 v40, v40, 2, v4
	ds_read_b32 v40, v40
	v_add_u32_e32 v41, 36, v3
	v_and_b32_e32 v41, 63, v41
	v_lshl_add_u32 v41, v41, 2, v4
	ds_read_b32 v41, v41
	v_add_u32_e32 v42, 37, v3
	v_and_b32_e32 v42, 63, v42
	v_lshl_add_u32 v42, v42, 2, v4
	ds_read_b32 v42, v42
	v_add_u32_e32 v43, 38, v3
	v_and_b32_e32 v43, 63, v43
	v_lshl_add_u32 v43, v43, 2, v4
	ds_read_b32 v43, v43
	v_add_u32_e32 v44, 39, v3
	v_and_b32_e32 v44, 63, v44
	v_lshl_add_u32 v44, v44, 2, v4
	ds_read_b32 v44, v44
	v_add_u32_e32 v45, 40, v3
	v_and_b32_e32 v45, 63, v45
	v_lshl_add_u32 v45, v45, 2, v4
	ds_read_b32 v45, v45
	s_waitcnt lgkmcnt(12)
; #define TIDX (tid_launder())
; DI void epi_rownorm(const float* Ct, float* rn, int W) {
;   const int row = TIDX >> 1, grp = TIDX & 1;
;   float ss = 0.f;
;   for (int c0 = 0; c0 < 64; ++c0) { const int c = (c0 + row) & 63; const float v = Ct[row * 132 + grp * 64 + c]; ss += v * v; }
;   if (W == 128) { ss += __shfl_xor(ss, 1); ss *= 0.5f; }
;   rn[row * 2 + grp] = rsqrtf(ss * (1.f / 64.f) + 1e-6f);
;   __syncthreads();
; }
; DI void epi_store64(const float* Ct, int cb, const float* rn, int grp, const float* gain, bool silu, const float* bias,
;                     bf16_t* dst, size_t ldd, int dcol0, int m0, int Mmax) {
;   const int tid = TIDX, c = (tid & 15) * 4;
;   float4 gv = make_float4(1.f, 1.f, 1.f, 1.f), bv = make_float4(0.f, 0.f, 0.f, 0.f);
;   if (rn) gv = *(const float4*)(gain + c);
	v_fmac_f32_e32 v5, v6, v6
	s_waitcnt lgkmcnt(11)
	v_fmac_f32_e32 v5, v34, v34
	s_waitcnt lgkmcnt(10)
	v_fmac_f32_e32 v5, v35, v35
	s_waitcnt lgkmcnt(9)
	v_fmac_f32_e32 v5, v36, v36
	s_waitcnt lgkmcnt(8)
	v_fmac_f32_e32 v5, v37, v37
	s_waitcnt lgkmcnt(7)
	v_fmac_f32_e32 v5, v38, v38
	s_waitcnt lgkmcnt(6)
	v_fmac_f32_e32 v5, v39, v39
	s_waitcnt lgkmcnt(5)
	v_fmac_f32_e32 v5, v40, v40
	s_waitcnt lgkmcnt(4)
	v_fmac_f32_e32 v5, v41, v41
	s_waitcnt lgkmcnt(3)
	v_fmac_f32_e32 v5, v42, v42
	s_waitcnt lgkmcnt(2)
	v_fmac_f32_e32 v5, v43, v43
	s_waitcnt lgkmcnt(1)
	v_fmac_f32_e32 v5, v44, v44
	s_waitcnt lgkmcnt(0)
	v_fmac_f32_e32 v5, v45, v45
	v_add_u32_e32 v6, 41, v3
	v_and_b32_e32 v6, 63, v6
	v_lshl_add_u32 v6, v6, 2, v4
	ds_read_b32 v6, v6
	v_add_u32_e32 v34, 42, v3
	v_and_b32_e32 v34, 63, v34
	v_lshl_add_u32 v34, v34, 2, v4
	ds_read_b32 v34, v34
	v_add_u32_e32 v35, 43, v3
	v_and_b32_e32 v35, 63, v35
	v_lshl_add_u32 v35, v35, 2, v4
	ds_read_b32 v35, v35
	v_add_u32_e32 v36, 44, v3
	v_and_b32_e32 v36, 63, v36
	v_lshl_add_u32 v36, v36, 2, v4
	ds_read_b32 v36, v36
	v_add_u32_e32 v37, 45, v3
	v_and_b32_e32 v37, 63, v37
	v_lshl_add_u32 v37, v37, 2, v4
	ds_read_b32 v37, v37
	v_add_u32_e32 v38, 46, v3
	v_and_b32_e32 v38, 63, v38
	v_lshl_add_u32 v38, v38, 2, v4
	ds_read_b32 v38, v38
	v_add_u32_e32 v39, 47, v3
	v_and_b32_e32 v39, 63, v39
	v_lshl_add_u32 v39, v39, 2, v4
	ds_read_b32 v39, v39
	v_add_u32_e32 v40, 48, v3
	v_and_b32_e32 v40, 63, v40
	v_lshl_add_u32 v40, v40, 2, v4
	ds_read_b32 v40, v40
	v_add_u32_e32 v41, 49, v3
	v_and_b32_e32 v41, 63, v41
	v_lshl_add_u32 v41, v41, 2, v4
	ds_read_b32 v41, v41
	v_add_u32_e32 v42, 50, v3
	v_and_b32_e32 v42, 63, v42
	v_lshl_add_u32 v42, v42, 2, v4
	ds_read_b32 v42, v42
	v_add_u32_e32 v43, 51, v3
	v_and_b32_e32 v43, 63, v43
	v_lshl_add_u32 v43, v43, 2, v4
	ds_read_b32 v43, v43
	v_add_u32_e32 v44, 52, v3
	v_and_b32_e32 v44, 63, v44
	v_lshl_add_u32 v44, v44, 2, v4
	ds_read_b32 v44, v44
	v_add_u32_e32 v45, 53, v3
	v_and_b32_e32 v45, 63, v45
	v_lshl_add_u32 v45, v45, 2, v4
	ds_read_b32 v45, v45
	s_waitcnt lgkmcnt(12)
	v_fmac_f32_e32 v5, v6, v6
	s_waitcnt lgkmcnt(11)
	v_fmac_f32_e32 v5, v34, v34
	s_waitcnt lgkmcnt(10)
	v_fmac_f32_e32 v5, v35, v35
	s_waitcnt lgkmcnt(9)
	v_fmac_f32_e32 v5, v36, v36
	s_waitcnt lgkmcnt(8)
	v_fmac_f32_e32 v5, v37, v37
	s_waitcnt lgkmcnt(7)
	v_fmac_f32_e32 v5, v38, v38
	s_waitcnt lgkmcnt(6)
	v_fmac_f32_e32 v5, v39, v39
	s_waitcnt lgkmcnt(5)
	v_fmac_f32_e32 v5, v40, v40
	s_waitcnt lgkmcnt(4)
	v_fmac_f32_e32 v5, v41, v41
	s_waitcnt lgkmcnt(3)
	v_fmac_f32_e32 v5, v42, v42
	s_waitcnt lgkmcnt(2)
	v_fmac_f32_e32 v5, v43, v43
	s_waitcnt lgkmcnt(1)
	v_fmac_f32_e32 v5, v44, v44
	s_waitcnt lgkmcnt(0)
	v_fmac_f32_e32 v5, v45, v45
	v_add_u32_e32 v6, 54, v3
	v_and_b32_e32 v6, 63, v6
	v_lshl_add_u32 v6, v6, 2, v4
	ds_read_b32 v6, v6
	s_waitcnt lgkmcnt(0)
	v_pk_mul_f32 v[6:7], v[6:7], v[6:7]
	s_nop 0
	v_add_f32_e32 v5, v5, v6
	v_add_f32_e32 v5, v5, v7
	v_add_u32_e32 v6, 56, v3
	v_add_u32_e32 v7, 57, v3
	v_and_b32_e32 v6, 63, v6
	v_and_b32_e32 v7, 63, v7
	v_lshl_add_u32 v6, v6, 2, v4
	v_lshl_add_u32 v7, v7, 2, v4
	ds_read_b32 v6, v6
	ds_read_b32 v7, v7
	s_waitcnt lgkmcnt(0)
	v_pk_mul_f32 v[6:7], v[6:7], v[6:7]
	s_nop 0
	v_add_f32_e32 v5, v5, v6
	v_add_f32_e32 v5, v5, v7
	v_add_u32_e32 v6, 58, v3
	v_add_u32_e32 v7, 59, v3
	v_and_b32_e32 v6, 63, v6
	v_and_b32_e32 v7, 63, v7
	v_lshl_add_u32 v6, v6, 2, v4
	v_lshl_add_u32 v7, v7, 2, v4
	ds_read_b32 v6, v6
	ds_read_b32 v7, v7
	s_waitcnt lgkmcnt(0)
	v_pk_mul_f32 v[6:7], v[6:7], v[6:7]
	s_nop 0
	v_add_f32_e32 v5, v5, v6
	v_add_f32_e32 v5, v5, v7
	v_add_u32_e32 v6, 60, v3
	v_add_u32_e32 v7, 61, v3
	v_and_b32_e32 v6, 63, v6
	v_and_b32_e32 v7, 63, v7
	v_lshl_add_u32 v6, v6, 2, v4
	v_lshl_add_u32 v7, v7, 2, v4
	ds_read_b32 v6, v6
	ds_read_b32 v7, v7
	s_waitcnt lgkmcnt(0)
	v_pk_mul_f32 v[6:7], v[6:7], v[6:7]
	s_nop 0
	v_add_f32_e32 v5, v5, v6
	v_add_f32_e32 v8, v5, v7
	v_add_u32_e32 v5, 62, v3
	v_add_u32_e32 v3, -1, v3
	v_and_b32_e32 v5, 63, v5
	v_and_b32_e32 v3, 63, v3
	v_lshl_add_u32 v5, v5, 2, v4
	v_lshl_add_u32 v3, v3, 2, v4
	ds_read_b32 v6, v5
	ds_read_b32 v7, v3
	s_waitcnt lgkmcnt(0)
	v_pk_mul_f32 v[4:5], v[6:7], v[6:7]
	s_nop 0
	v_add_f32_e32 v3, v8, v4
	v_add_f32_e32 v3, v3, v5
	v_fmamk_f32 v3, v3, 0x3c800000, v231
	v_cmp_gt_f32_e32 vcc, s0, v3
	v_mul_f32_e32 v4, 0x4b800000, v3
	s_mov_b32 s0, 0x3ffffffe
	v_cndmask_b32_e32 v3, v3, v4, vcc
	v_rsq_f32_e32 v3, v3
	v_and_or_b32 v0, v0, s0, v2
	v_lshl_add_u32 v0, v0, 2, v237
	v_mul_f32_e32 v4, 0x45800000, v3
	v_cndmask_b32_e32 v3, v3, v4, vcc
	ds_write_b32 v0, v3
	s_waitcnt lgkmcnt(0)
	s_barrier
	v_cndmask_b32_e64 v3, 0, 1, s[4:5]
	v_ashrrev_i32_e32 v0, 2, v18
	v_and_b32_e32 v2, -8, v0
	v_cmp_ne_u32_e64 s[0:1], 1, v3
	v_ashrrev_i32_e32 v3, 31, v2
	v_lshl_add_u64 v[4:5], v[2:3], 2, s[2:3]
	global_load_dword v10, v[4:5], off
	s_and_b64 vcc, exec, s[0:1]
	s_cbranch_vccnz .LBB0_1265
	v_lshl_add_u64 v[4:5], v[2:3], 2, s[2:3]
	global_load_dword v11, v[4:5], off offset:4
